# attention: software-pipelined K/V/Q global loads (next kv-head iteration prefetched into spare VGPRs mid-iteration)
# speedup vs baseline: 1.0040x; 1.0040x over previous
; #define LAS __attribute__((address_space(3)))
; __device__ __forceinline__ int crow(int r, int hi) { return (r & 3) + 8 * (r >> 2) + 4 * hi; }
; __device__ __forceinline__ void attn_phase(LAS unsigned char* lds, int vcu, int G, const bf16* Qp, const bf16* Kp, const bf16* Vt, const float* sinks, bf16* AO, int ldo, float* st) {
;     ...
;     const int lane = tid & 63, wave = __builtin_amdgcn_readfirstlane(tid >> 6), r32 = lane & 31, hi = lane >> 5, hq = wave & 3, qsub = wave >> 2;
;     const float NEG = -INFINITY;
;     float ssq_acc = 0.f;
;     for (int it = 0; it < 4; ++it) { const int id = ((vcu >> 5) << 7) | (it << 5) | (vcu & 31);
;         const int b = id >> 7, kvh = (id >> 5) & 3, q0 = 64 * (id & 31), h = kvh * 4 + hq;
;         const size_t tok0 = (size_t)b * SEQ;
;         const int jt0 = (q0 >= 128) ? 0 : (128 - q0) / 32;
;         v4u kv[3], vv[3];
; #pragma unroll
;         for (int i = 0; i < 3; ++i) { const int c = tid + 512 * i, row = c >> 3, ch = c & 7, key = q0 - 128 + row;
;             if (key >= 0) kv[i] = *(const v4u*)(Kp + (tok0 + key) * D_KV + kvh * HD + ch * 8); }
; #pragma unroll
;         for (int i = 0; i < 3; ++i) { const int c = tid + 512 * i, d = c / 24, ch = c - d * 24, key0 = q0 - 128 + 8 * ch;
;             if (key0 >= 0) vv[i] = *(const v4u*)(Vt + (size_t)(kvh * HD + d) * M + tok0 + key0); }
;         const bf16* qrow = Qp + (tok0 + q0 + 32 * qsub + r32) * D_ATTN + h * HD + 32 * hi;
;         bf16x8 qf[4];
; #pragma unroll
;         for (int kk = 0; kk < 4; ++kk) qf[kk] = *(const bf16x8*)(qrow + 8 * kk);
; #pragma unroll
;         for (int i = 0; i < 3; ++i) { const int c = tid + 512 * i, row = c >> 3, ch = c & 7, key = q0 - 128 + row;
;             if (key >= 0) *(LAS v4u*)(lds + row * AT_KROW + ch * 16) = kv[i]; }
; #pragma unroll
;         for (int i = 0; i < 3; ++i) { const int c = tid + 512 * i, d = c / 24, ch = c - d * 24, key0 = q0 - 128 + 8 * ch;
;             if (key0 >= 0) { LAS u64* p = (LAS u64*)(lds + AT_V_OFF + d * AT_VROW + ch * 16); p[0] = ((u64)vv[i].y << 32) | vv[i].x; p[1] = ((u64)vv[i].w << 32) | vv[i].z; } }
;     ...
;         for (int r = 0; r < 16; ++r) { const int cr = crow(r, hi); if (!(cr > r32)) s[0][r] = NEG; if (!(cr <= r32)) s[4][r] = NEG; }
.LBB0_654:
	v_writelane_b32 v254, s88, 53
	v_mov_b32_e32 v4, v0
	s_mov_b32 s15, 0x2aaaaaab
	v_writelane_b32 v254, s89, 54
	v_writelane_b32 v254, s2, 55
	v_readfirstlane_b32 s68, v4
	s_lshr_b32 s0, s68, 6
	v_writelane_b32 v254, s3, 56
	v_writelane_b32 v254, s0, 57
	s_lshl_b32 s0, s90, 6
	v_mul_hi_i32 v9, v4, s15
	s_bfe_i32 s66, s90, 0x190005
	s_and_b32 s3, s0, 0x7c0
	v_add_u32_e32 v8, 0x200, v4
	v_lshrrev_b32_e32 v13, 31, v9
	v_ashrrev_i32_e32 v9, 2, v9
	s_ashr_i32 s67, s66, 31
	v_mov_b32_e32 v3, s3
	s_sub_i32 s0, 0x80, s3
	v_add_u32_e32 v16, v9, v13
	v_mul_hi_i32 v9, v8, s15
	s_ashr_i32 s2, s68, 8
	s_lshl_b64 s[62:63], s[66:67], 11
	v_sub_co_u32_e32 v3, vcc, 0x7f, v3
	s_lshr_b32 s4, s0, 5
	v_lshrrev_b32_e32 v13, 31, v9
	v_ashrrev_i32_e32 v9, 2, v9
	s_and_b64 s[0:1], vcc, exec
	s_movk_i32 s16, 0xffe8
	v_add_u32_e32 v22, v9, v13
	s_cselect_b32 s28, 0, s4
	v_ashrrev_i32_e32 v25, 3, v8
	v_mad_u64_u32 v[8:9], s[4:5], v22, s16, v[8:9]
	s_add_i32 s14, s3, 0xffffff80
	v_lshlrev_b32_e32 v9, 3, v8
	v_add_u32_e32 v12, 0x400, v4
	v_add_u32_e32 v13, s14, v9
	v_cmp_lt_i32_e64 s[12:13], -1, v13
	v_mul_hi_i32 v13, v12, s15
	v_bfe_u32 v141, v4, 5, 1
	v_lshlrev_b32_e32 v5, 4, v4
	v_lshrrev_b32_e32 v24, 31, v13
	v_ashrrev_i32_e32 v13, 2, v13
	s_lshl_b32 s76, s2, 5
	v_and_b32_e32 v26, 0x70, v5
	v_lshlrev_b32_e32 v5, 2, v141
	v_add_u32_e32 v24, v13, v24
	s_ashr_i32 s77, s76, 31
	v_ashrrev_i32_e32 v30, 3, v12
	v_mad_u64_u32 v[18:19], s[4:5], v16, s16, v[4:5]
	v_mad_u64_u32 v[12:13], s[4:5], v24, s16, v[12:13]
	v_ashrrev_i32_e32 v23, 3, v4
	v_lshlrev_b32_e32 v19, 3, v18
	v_lshlrev_b32_e32 v13, 3, v12
	s_movk_i32 s5, 0x188
	s_cmp_ge_i32 s2, s28
	v_add_u32_e32 v20, s14, v19
	v_cmp_gt_i32_e64 s[16:17], v23, v3
	v_cmp_gt_i32_e64 s[18:19], v25, v3
	v_cmp_gt_i32_e64 s[20:21], v30, v3
	v_cmp_gt_i32_e64 s[22:23], v19, v3
	v_mul_lo_u32 v19, v16, s5
	v_cmp_gt_i32_e64 s[24:25], v9, v3
	v_mul_lo_u32 v9, v22, s5
	v_cmp_gt_i32_e64 s[26:27], v13, v3
	v_mul_lo_u32 v3, v24, s5
	s_cselect_b64 s[82:83], -1, 0
	s_add_i32 s5, s2, 1
	s_cmp_ge_i32 s5, s28
	v_and_b32_e32 v140, 31, v4
	s_cselect_b64 s[72:73], -1, 0
	s_add_i32 s60, s2, 2
	s_movk_i32 s4, 0x90
	v_lshlrev_b32_e32 v34, 4, v8
	v_or_b32_e32 v8, s76, v140
	s_cmp_ge_i32 s60, s28
	v_mul_lo_u32 v36, v8, s4
	v_lshl_or_b32 v8, s5, 5, v140
	s_cselect_b64 s[88:89], -1, 0
	s_add_i32 s69, s2, 3
	v_mul_lo_u32 v37, v8, s4
	v_lshl_or_b32 v8, s60, 5, v140
	s_cmp_ge_i32 s69, s28
	v_mul_lo_u32 v38, v8, s4
	s_cselect_b64 s[96:97], -1, 0
	v_lshl_or_b32 v8, s69, 5, v140
	s_add_i32 s70, s2, 4
	v_mul_lo_u32 v39, v8, s4
	v_lshl_or_b32 v8, s70, 5, v140
	v_mul_lo_u32 v40, v8, s4
	v_or_b32_e32 v8, 2, v5
	v_cmp_gt_u32_e64 s[34:35], v8, v140
	v_or_b32_e32 v8, 3, v5
	v_cmp_gt_u32_e64 s[36:37], v8, v140
	v_or_b32_e32 v8, 8, v5
	v_cmp_gt_u32_e64 s[38:39], v8, v140
	v_or_b32_e32 v8, 9, v5
	v_cmp_gt_u32_e64 s[40:41], v8, v140
	v_or_b32_e32 v8, 10, v5
	v_cmp_gt_u32_e64 s[42:43], v8, v140
	v_or_b32_e32 v8, 11, v5
	v_cmp_gt_u32_e64 s[44:45], v8, v140
	v_or_b32_e32 v8, 16, v5
	v_cmp_gt_u32_e64 s[46:47], v8, v140
	v_or_b32_e32 v8, 17, v5
	v_cmp_gt_u32_e64 s[48:49], v8, v140
	v_or_b32_e32 v8, 18, v5
	v_lshlrev_b32_e32 v28, 6, v141
	v_cmp_gt_u32_e64 s[50:51], v8, v140
	v_or_b32_e32 v8, 19, v5
	v_add_u32_e32 v29, 0, v28
	s_movk_i32 s0, 0xffc8
	v_cmp_gt_u32_e64 s[52:53], v8, v140
	v_or_b32_e32 v8, 24, v5
	v_mad_i32_i24 v17, v141, s0, v29
	v_add_u32_e32 v31, s14, v13
	v_cmp_gt_u32_e64 s[54:55], v8, v140
	v_or_b32_e32 v8, 25, v5
	v_add_u32_e32 v6, s14, v23
	v_add_u32_e32 v10, s14, v25
	v_add_u32_e32 v14, s14, v30
	v_cmp_lt_i32_e64 s[14:15], -1, v31
	v_mul_lo_u32 v31, v23, s4
	v_mul_lo_u32 v32, v25, s4
	s_cmp_ge_i32 s70, s28
	v_cmp_gt_u32_e64 s[56:57], v8, v140
	v_or_b32_e32 v8, 26, v5
	v_lshl_add_u32 v41, s5, 6, v17
	v_lshl_add_u32 v42, s60, 6, v17
	v_lshl_add_u32 v43, s2, 6, v17
	v_lshl_add_u32 v45, s69, 6, v17
	v_lshl_add_u32 v46, s70, 6, v17
	v_ashrrev_i32_e32 v17, 31, v16
	v_ashrrev_i32_e32 v23, 31, v22
	v_ashrrev_i32_e32 v25, 31, v24
	v_mul_lo_u32 v30, v30, s4
	v_add_u32_e32 v33, 0, v9
	v_lshlrev_b32_e32 v35, 4, v12
	s_cselect_b64 s[74:75], -1, 0
	v_cmp_gt_u32_e64 s[58:59], v8, v140
	v_lshlrev_b64 v[8:9], 15, v[16:17]
	s_lshl_b64 s[4:5], s[66:67], 12
	v_lshlrev_b64 v[12:13], 15, v[22:23]
	v_lshlrev_b64 v[16:17], 15, v[24:25]
	v_mov_b32_e32 v21, v2
	v_cmp_gt_u32_e64 s[28:29], v5, v140
	v_cmp_lt_u32_e64 s[30:31], v5, v140
	v_or_b32_e32 v5, 27, v5
	v_lshl_add_u64 v[8:9], v[8:9], 0, s[4:5]
	v_lshl_add_u64 v[12:13], v[12:13], 0, s[4:5]
	v_lshl_add_u64 v[16:17], v[16:17], 0, s[4:5]
	s_movk_i32 s4, 0xc0
	v_cmp_lt_i32_e64 s[10:11], -1, v20
	v_cmp_gt_u32_e64 s[60:61], v5, v140
	v_lshl_add_u64 v[8:9], v[20:21], 1, v[8:9]
	v_mul_lo_u32 v5, v22, s4
	v_mul_lo_u32 v20, v24, s4
	s_mov_b64 s[4:5], 0xd800000
	v_lshl_add_u64 v[124:125], v[8:9], 0, s[4:5]
	v_lshl_add_u32 v8, v4, 3, s3
	v_sub_u32_e32 v4, v8, v5
	v_add_u32_e32 v4, 0xf80, v4
	v_mov_b32_e32 v5, v2
	v_lshl_add_u64 v[4:5], v[4:5], 1, v[12:13]
	v_lshl_add_u64 v[126:127], v[4:5], 0, s[4:5]
	v_sub_u32_e32 v4, v8, v20
	v_add_u32_e32 v4, 0x1f80, v4
	v_mov_b32_e32 v5, v2
	v_mov_b32_e32 v7, v2
	v_lshl_add_u64 v[4:5], v[4:5], 1, v[16:17]
	v_lshl_add_u64 v[128:129], v[4:5], 0, s[4:5]
	s_lshl_b64 s[4:5], s[66:67], 20
	v_lshlrev_b64 v[4:5], 9, v[6:7]
	v_lshl_add_u64 v[4:5], s[4:5], 0, v[4:5]
	v_mov_b32_e32 v11, v2
	v_or_b32_e32 v4, v4, v26
	s_mov_b64 s[66:67], 0xd000000
	v_lshl_add_u64 v[130:131], v[4:5], 0, s[66:67]
	v_lshlrev_b64 v[4:5], 9, v[10:11]
	v_lshl_add_u64 v[4:5], s[4:5], 0, v[4:5]
	v_mov_b32_e32 v15, v2
	v_or_b32_e32 v4, v4, v26
	v_lshl_add_u64 v[132:133], v[4:5], 0, s[66:67]
	v_lshlrev_b64 v[4:5], 9, v[14:15]
; __device__ __forceinline__ unsigned cvt_pk_bf16(float lo, float hi) { unsigned r; asm volatile("v_cvt_pk_bf16_f32 %0, %1, %2" : "=v"(r) : "v"(lo), "v"(hi)); return r; }
; #define LDS_WAIT() asm volatile("s_waitcnt lgkmcnt(0)" ::: "memory")
; __device__ __forceinline__ void attn_phase(LAS unsigned char* lds, int vcu, int G, const bf16* Qp, const bf16* Kp, const bf16* Vt, const float* sinks, bf16* AO, int ldo, float* st) {
;     ...
;         v4u kv[3], vv[3];
; #pragma unroll
;         for (int i = 0; i < 3; ++i) { const int c = tid + 512 * i, row = c >> 3, ch = c & 7, key = q0 - 128 + row;
;             if (key >= 0) kv[i] = *(const v4u*)(Kp + (tok0 + key) * D_KV + kvh * HD + ch * 8); }
; #pragma unroll
;         for (int i = 0; i < 3; ++i) { const int c = tid + 512 * i, d = c / 24, ch = c - d * 24, key0 = q0 - 128 + 8 * ch;
;             if (key0 >= 0) vv[i] = *(const v4u*)(Vt + (size_t)(kvh * HD + d) * M + tok0 + key0); }
;         const bf16* qrow = Qp + (tok0 + q0 + 32 * qsub + r32) * D_ATTN + h * HD + 32 * hi;
;         bf16x8 qf[4];
; #pragma unroll
;         for (int kk = 0; kk < 4; ++kk) qf[kk] = *(const bf16x8*)(qrow + 8 * kk);
;     ...
;         {
;             float ssq = 0.f;
; #pragma unroll
;             for (int dh = 0; dh < 2; ++dh)
; #pragma unroll
;                 for (int r = 0; r < 16; ++r) ssq += o[dh][r] * o[dh][r];
;             ssq += __shfl_xor(ssq, 32);
;             ssq_acc += ssq;
;         }
;         bf16* orow = AO + (tok0 + q0 + 32 * qsub + r32) * (size_t)ldo + h * HD + 4 * hi;
; #pragma unroll
;         for (int dh = 0; dh < 2; ++dh)
; #pragma unroll
;             for (int g4 = 0; g4 < 4; ++g4) { v2u w; w.x = cvt_pk_bf16(o[dh][4 * g4], o[dh][4 * g4 + 1]); w.y = cvt_pk_bf16(o[dh][4 * g4 + 2], o[dh][4 * g4 + 3]);
;                 *(v2u*)(orow + dh * 32 + 8 * g4) = w; }
;         LDS_WAIT(); __syncthreads();
	v_lshl_add_u64 v[4:5], s[4:5], 0, v[4:5]
	s_lshr_b32 s4, s68, 4
	s_and_b32 s4, s4, 12
	s_add_u32 s4, s64, s4
	s_addc_u32 s5, s65, 0
	v_writelane_b32 v254, s90, 58
	v_or_b32_e32 v4, v4, v26
	s_add_u32 s62, s62, s76
	v_lshl_add_u64 v[134:135], v[4:5], 0, s[66:67]
	v_writelane_b32 v254, s76, 59
	s_addc_u32 s63, s63, s77
	v_or_b32_e32 v4, s3, v140
	v_mov_b32_e32 v5, v2
	v_lshl_add_u64 v[4:5], s[62:63], 0, v[4:5]
	s_lshl_b32 s62, s68, 1
	v_cmp_lt_i32_e64 s[0:1], -1, v6
	v_lshlrev_b64 v[6:7], 12, v[4:5]
	s_and_b32 s64, s62, 0x180
	v_lshlrev_b32_e32 v8, 3, v141
	v_or3_b32 v6, v6, s64, v8
	s_mov_b64 s[62:63], 0xf000040
	v_lshlrev_b64 v[4:5], 11, v[4:5]
	v_lshl_add_u64 v[136:137], v[6:7], 0, s[62:63]
	v_or3_b32 v4, v4, s64, v28
	s_mov_b64 s[62:63], 0xb000020
	v_add_u32_e32 v27, 0, v26
	v_add_u32_e32 v19, 0, v19
	v_lshlrev_b32_e32 v18, 4, v18
	v_add_u32_e32 v3, 0, v3
	v_mul_u32_u24_e32 v44, 0x188, v140
	v_writelane_b32 v254, s77, 60
	v_lshl_add_u64 v[138:139], v[4:5], 0, s[62:63]
	s_movk_i32 s62, 0x6c00
	v_cmp_lt_i32_e64 s[6:7], -1, v10
	v_cmp_lt_i32_e64 s[8:9], -1, v14
	v_writelane_b32 v254, s3, 61
	s_mov_b64 s[76:77], 0
	v_add_u32_e32 v142, v27, v31
	v_add_u32_e32 v143, v27, v32
	v_add_u32_e32 v144, v27, v30
	v_add3_u32 v145, v19, v18, s62
	v_add3_u32 v146, v33, v34, s62
	v_add3_u32 v147, v3, v35, s62
	v_add_u32_e32 v148, v29, v36
	v_add_u32_e32 v149, v29, v37
	v_add_u32_e32 v150, v29, v38
	v_add_u32_e32 v151, v29, v39
	v_add_u32_e32 v152, v29, v40
	v_mbcnt_hi_u32_b32 v1, -1, v1
	v_add_u32_e32 v153, v43, v44
	v_add_u32_e32 v154, v41, v44
	v_add_u32_e32 v155, v42, v44
	v_add_u32_e32 v156, v45, v44
	v_add_u32_e32 v157, v46, v44
	s_mov_b64 s[78:79], 0x200000
	s_mov_b64 s[90:91], 0x80
	v_mov_b32_e32 v158, 0xff800000
	v_mov_b32_e32 v159, 0
	s_mov_b32 s3, 0x3fb8aa3b
	s_mov_b64 exec, s[0:1]
	v_lshl_add_u64 v[240:241], s[94:95], 0, v[130:131]
	global_load_dwordx4 v[200:203], v[240:241], off
	s_mov_b64 exec, s[6:7]
	v_lshl_add_u64 v[240:241], s[94:95], 0, v[132:133]
	global_load_dwordx4 v[204:207], v[240:241], off
	s_mov_b64 exec, s[8:9]
	v_lshl_add_u64 v[240:241], s[94:95], 0, v[134:135]
	global_load_dwordx4 v[208:211], v[240:241], off
	s_mov_b64 exec, s[10:11]
	v_lshl_add_u64 v[240:241], s[94:95], 0, v[124:125]
	global_load_dwordx4 v[212:215], v[240:241], off
	s_mov_b64 exec, s[12:13]
	v_lshl_add_u64 v[240:241], s[94:95], 0, v[126:127]
	global_load_dwordx4 v[216:219], v[240:241], off
	s_mov_b64 exec, s[14:15]
	v_lshl_add_u64 v[240:241], s[94:95], 0, v[128:129]
	global_load_dwordx4 v[220:223], v[240:241], off
	s_mov_b64 exec, -1
	v_lshl_add_u64 v[240:241], s[94:95], 0, v[138:139]
	global_load_dwordx4 v[224:227], v[240:241], off offset:-32
	global_load_dwordx4 v[228:231], v[240:241], off offset:-16
	global_load_dwordx4 v[232:235], v[240:241], off
	global_load_dwordx4 v[236:239], v[240:241], off offset:16
	s_branch .LBB0_656
.LBB0_655:
	s_nop 7
	v_mul_f32_e32 v3, v35, v35
	v_fmac_f32_e32 v3, v34, v34
	v_fmac_f32_e32 v3, v36, v36
	v_fmac_f32_e32 v3, v37, v37
	v_fmac_f32_e32 v3, v38, v38
	v_fmac_f32_e32 v3, v39, v39
	v_fmac_f32_e32 v3, v40, v40
	v_fmac_f32_e32 v3, v41, v41
	v_fmac_f32_e32 v3, v42, v42
	v_fmac_f32_e32 v3, v43, v43
	v_fmac_f32_e32 v3, v44, v44
	v_fmac_f32_e32 v3, v45, v45
	v_fmac_f32_e32 v3, v46, v46
	v_fmac_f32_e32 v3, v47, v47
	v_fmac_f32_e32 v3, v48, v48
	v_fmac_f32_e32 v3, v49, v49
	v_fmac_f32_e32 v3, v18, v18
	v_fmac_f32_e32 v3, v19, v19
	v_fmac_f32_e32 v3, v20, v20
	v_fmac_f32_e32 v3, v21, v21
	v_fmac_f32_e32 v3, v22, v22
	v_fmac_f32_e32 v3, v23, v23
	v_pk_mul_f32 v[12:13], v[24:25], v[24:25]
	v_pk_mul_f32 v[10:11], v[26:27], v[26:27]
	v_add_f32_e32 v3, v12, v3
	v_add_f32_e32 v3, v13, v3
	v_add_f32_e32 v3, v10, v3
	v_pk_mul_f32 v[8:9], v[28:29], v[28:29]
	v_add_f32_e32 v3, v11, v3
	v_add_f32_e32 v3, v8, v3
	v_pk_mul_f32 v[6:7], v[30:31], v[30:31]
	v_add_f32_e32 v3, v9, v3
	v_add_f32_e32 v3, v6, v3
	v_pk_mul_f32 v[4:5], v[32:33], v[32:33]
	v_add_f32_e32 v3, v7, v3
	v_add_f32_e32 v3, v4, v3
	v_add_f32_e32 v3, v5, v3
	ds_bpermute_b32 v4, v172, v3
	v_cvt_pk_bf16_f32 v6, v34, v35
	v_cvt_pk_bf16_f32 v7, v36, v37
	s_add_u32 s76, s76, 16
	s_addc_u32 s77, s77, 0
	s_waitcnt lgkmcnt(0)
	v_add_f32_e32 v3, v3, v4
	v_lshl_add_u64 v[4:5], s[94:95], 0, v[136:137]
	global_store_dwordx2 v[4:5], v[6:7], off offset:-64
	v_cvt_pk_bf16_f32 v6, v38, v39
	v_cvt_pk_bf16_f32 v7, v40, v41
	global_store_dwordx2 v[4:5], v[6:7], off offset:-48
	v_cvt_pk_bf16_f32 v6, v42, v43
	v_cvt_pk_bf16_f32 v7, v44, v45
	global_store_dwordx2 v[4:5], v[6:7], off offset:-32
	v_cvt_pk_bf16_f32 v6, v46, v47
	v_cvt_pk_bf16_f32 v7, v48, v49
	global_store_dwordx2 v[4:5], v[6:7], off offset:-16
	v_cvt_pk_bf16_f32 v6, v18, v19
	v_cvt_pk_bf16_f32 v7, v20, v21
	global_store_dwordx2 v[4:5], v[6:7], off
	v_cvt_pk_bf16_f32 v6, v22, v23
	v_cvt_pk_bf16_f32 v7, v24, v25
	global_store_dwordx2 v[4:5], v[6:7], off offset:16
	v_cvt_pk_bf16_f32 v6, v26, v27
	v_cvt_pk_bf16_f32 v7, v28, v29
	global_store_dwordx2 v[4:5], v[6:7], off offset:32
	v_cvt_pk_bf16_f32 v6, v30, v31
	v_cvt_pk_bf16_f32 v7, v32, v33
	global_store_dwordx2 v[4:5], v[6:7], off offset:48
	s_waitcnt lgkmcnt(0)
	v_add_f32_e32 v159, v159, v3
	v_lshl_add_u64 v[136:137], v[136:137], 0, s[86:87]
	s_cmp_eq_u32 s76, 64
	s_barrier
	s_cbranch_scc1 .LBB0_700
.LBB0_656:
	s_waitcnt vmcnt(0)
	v_mov_b32_e32 v120, v224
	v_mov_b32_e32 v121, v225
	v_mov_b32_e32 v122, v226
	v_mov_b32_e32 v123, v227
	v_mov_b32_e32 v116, v228
	v_mov_b32_e32 v117, v229
	v_mov_b32_e32 v118, v230
	v_mov_b32_e32 v119, v231
	v_mov_b32_e32 v112, v232
	v_mov_b32_e32 v113, v233
	v_mov_b32_e32 v114, v234
	v_mov_b32_e32 v115, v235
	v_mov_b32_e32 v108, v236
	v_mov_b32_e32 v109, v237
	v_mov_b32_e32 v110, v238
	v_mov_b32_e32 v111, v239
	s_and_saveexec_b64 s[62:63], s[16:17]
	s_cbranch_execnz .LBB0_687
	s_or_b64 exec, exec, s[62:63]
	s_and_saveexec_b64 s[62:63], s[18:19]
	s_cbranch_execnz .LBB0_688

; #define LAS __attribute__((address_space(3)))
; __device__ __forceinline__ void attn_phase(LAS unsigned char* lds, int vcu, int G, const bf16* Qp, const bf16* Kp, const bf16* Vt, const float* sinks, bf16* AO, int ldo, float* st) {
;     ...
;         for (int i = 0; i < 3; ++i) { const int c = tid + 512 * i, d = c / 24, ch = c - d * 24, key0 = q0 - 128 + 8 * ch;
;             if (key0 >= 0) { LAS u64* p = (LAS u64*)(lds + AT_V_OFF + d * AT_VROW + ch * 16); p[0] = ((u64)vv[i].y << 32) | vv[i].x; p[1] = ((u64)vv[i].w << 32) | vv[i].z; } }
.LBB0_669:
	s_waitcnt vmcnt(0)
	ds_write2_b64 v147, v[220:221], v[222:223] offset1:1

; __device__ __forceinline__ int crow(int r, int hi) { return (r & 3) + 8 * (r >> 2) + 4 * hi; }
; __device__ __forceinline__ void attn_phase(LAS unsigned char* lds, int vcu, int G, const bf16* Qp, const bf16* Kp, const bf16* Vt, const float* sinks, bf16* AO, int ldo, float* st) {
;     ...
;         for (int i = 0; i < 3; ++i) { const int c = tid + 512 * i, row = c >> 3, ch = c & 7, key = q0 - 128 + row;
;             if (key >= 0) kv[i] = *(const v4u*)(Kp + (tok0 + key) * D_KV + kvh * HD + ch * 8); }
; #pragma unroll
;         for (int i = 0; i < 3; ++i) { const int c = tid + 512 * i, d = c / 24, ch = c - d * 24, key0 = q0 - 128 + 8 * ch;
;             if (key0 >= 0) vv[i] = *(const v4u*)(Vt + (size_t)(kvh * HD + d) * M + tok0 + key0); }
;         const bf16* qrow = Qp + (tok0 + q0 + 32 * qsub + r32) * D_ATTN + h * HD + 32 * hi;
;         bf16x8 qf[4];
; #pragma unroll
;         for (int kk = 0; kk < 4; ++kk) qf[kk] = *(const bf16x8*)(qrow + 8 * kk);
;     ...
;         for (int r = 0; r < 16; ++r) { const int cr = crow(r, hi); if (!(cr > r32)) s[0][r] = NEG; if (!(cr <= r32)) s[4][r] = NEG; }
;         const float sk = sinks[h] * 1.4426950408889634f;
;         float mx = sk;
; #pragma unroll
;         for (int kt = 0; kt < 5; ++kt)
; #pragma unroll
;             for (int r = 0; r < 16; ++r) mx = fmaxf(mx, s[kt][r]);
.LBB0_680:
	s_add_u32 vcc_lo, s4, s76
	s_addc_u32 vcc_hi, s5, s77
	global_load_dword v183, v2, vcc
	s_nop 8
	v_cndmask_b32_e64 v185, v70, v158, s[34:35]
	v_and_b32_e32 v70, 64, v1
	v_cndmask_b32_e64 v184, v158, v69, s[30:31]
	v_xor_b32_e32 v69, 32, v1
	v_add_u32_e32 v173, 64, v70
	v_cndmask_b32_e64 v3, v68, v158, s[28:29]
	v_cmp_lt_i32_e32 vcc, v69, v173
	v_cndmask_b32_e64 v198, v3, v68, s[30:31]
	v_cndmask_b32_e64 v52, v158, v52, s[28:29]
	v_cndmask_b32_e32 v3, v1, v69, vcc
	v_cndmask_b32_e64 v53, v53, v158, s[30:31]
	v_lshlrev_b32_e32 v172, 2, v3
	v_cndmask_b32_e64 v54, v158, v54, s[34:35]
	v_cndmask_b32_e64 v55, v158, v55, s[36:37]
	v_cndmask_b32_e64 v56, v158, v56, s[38:39]
	v_cndmask_b32_e64 v57, v158, v57, s[40:41]
	v_cndmask_b32_e64 v58, v158, v58, s[42:43]
	v_cndmask_b32_e64 v59, v158, v59, s[44:45]
	v_cndmask_b32_e64 v60, v158, v60, s[46:47]
	v_cndmask_b32_e64 v61, v158, v61, s[48:49]
	v_cndmask_b32_e64 v62, v158, v62, s[50:51]
	v_cndmask_b32_e64 v63, v158, v63, s[52:53]
	v_cndmask_b32_e64 v64, v158, v64, s[54:55]
	v_cndmask_b32_e64 v65, v158, v65, s[56:57]
	v_cndmask_b32_e64 v66, v158, v66, s[58:59]
	v_cndmask_b32_e64 v67, v158, v67, s[60:61]
	v_cndmask_b32_e64 v186, v71, v158, s[36:37]
	v_cndmask_b32_e64 v187, v72, v158, s[38:39]
	v_cndmask_b32_e64 v188, v73, v158, s[40:41]
	v_cndmask_b32_e64 v189, v74, v158, s[42:43]
	v_cndmask_b32_e64 v190, v75, v158, s[44:45]
	v_cndmask_b32_e64 v191, v76, v158, s[46:47]
	v_cndmask_b32_e64 v192, v77, v158, s[48:49]
	v_cndmask_b32_e64 v193, v78, v158, s[50:51]
	v_cndmask_b32_e64 v194, v79, v158, s[52:53]
	v_cndmask_b32_e64 v195, v80, v158, s[54:55]
	v_cndmask_b32_e64 v81, v81, v158, s[56:57]
	v_cndmask_b32_e64 v196, v82, v158, s[58:59]
	v_cndmask_b32_e64 v197, v83, v158, s[60:61]
	s_waitcnt vmcnt(0)
	s_cmp_eq_u32 s76, 48
	s_cbranch_scc1 .Lattn_pf_skip
	v_lshl_add_u64 v[124:125], v[124:125], 0, s[78:79]
	v_lshl_add_u64 v[126:127], v[126:127], 0, s[78:79]
	v_lshl_add_u64 v[128:129], v[128:129], 0, s[78:79]
	v_lshl_add_u64 v[130:131], v[130:131], 0, s[90:91]
	v_lshl_add_u64 v[132:133], v[132:133], 0, s[90:91]
	v_lshl_add_u64 v[134:135], v[134:135], 0, s[90:91]
	v_lshl_add_u64 v[138:139], v[138:139], 0, s[86:87]
	s_mov_b64 exec, s[0:1]
	v_lshl_add_u64 v[240:241], s[94:95], 0, v[130:131]
	global_load_dwordx4 v[200:203], v[240:241], off
	s_mov_b64 exec, s[6:7]
	v_lshl_add_u64 v[240:241], s[94:95], 0, v[132:133]
	global_load_dwordx4 v[204:207], v[240:241], off
	s_mov_b64 exec, s[8:9]
	v_lshl_add_u64 v[240:241], s[94:95], 0, v[134:135]
	global_load_dwordx4 v[208:211], v[240:241], off
	s_mov_b64 exec, s[10:11]
	v_lshl_add_u64 v[240:241], s[94:95], 0, v[124:125]
	global_load_dwordx4 v[212:215], v[240:241], off
	s_mov_b64 exec, s[12:13]
	v_lshl_add_u64 v[240:241], s[94:95], 0, v[126:127]
	global_load_dwordx4 v[216:219], v[240:241], off
	s_mov_b64 exec, s[14:15]
	v_lshl_add_u64 v[240:241], s[94:95], 0, v[128:129]
	global_load_dwordx4 v[220:223], v[240:241], off
	s_mov_b64 exec, -1
	v_lshl_add_u64 v[240:241], s[94:95], 0, v[138:139]
	global_load_dwordx4 v[224:227], v[240:241], off offset:-32
	global_load_dwordx4 v[228:231], v[240:241], off offset:-16
	global_load_dwordx4 v[232:235], v[240:241], off
	global_load_dwordx4 v[236:239], v[240:241], off offset:16
.Lattn_pf_skip:
	v_mul_f32_e32 v3, 0x3fb8aa3b, v183
	v_max3_f32 v3, v3, v52, v53
	v_max3_f32 v3, v3, v54, v55
	v_max3_f32 v3, v3, v56, v57
	v_max3_f32 v3, v3, v58, v59
	v_max3_f32 v3, v3, v60, v61
	v_max3_f32 v3, v3, v62, v63
	v_max3_f32 v3, v3, v64, v65
	v_max3_f32 v3, v3, v66, v67
	v_max3_f32 v3, v3, v4, v5
	v_max3_f32 v3, v3, v6, v7
	v_max3_f32 v3, v3, v8, v9
	v_max3_f32 v3, v3, v10, v11
	v_max3_f32 v3, v3, v12, v13
	v_max3_f32 v3, v3, v14, v15
	v_max3_f32 v3, v3, v16, v17
	v_max3_f32 v3, v3, v18, v19
	v_max3_f32 v3, v3, v36, v37
	v_max3_f32 v3, v3, v38, v39
	v_max3_f32 v3, v3, v40, v41
	v_max3_f32 v3, v3, v42, v43
	v_max3_f32 v3, v3, v44, v45
	v_max3_f32 v3, v3, v46, v47
	v_max3_f32 v3, v3, v48, v49
	v_max3_f32 v3, v3, v50, v51
	v_max3_f32 v3, v3, v20, v21
	v_max3_f32 v3, v3, v22, v23
	v_max3_f32 v3, v3, v24, v25
	v_max3_f32 v3, v3, v26, v27
	v_max3_f32 v3, v3, v28, v29
	v_max3_f32 v3, v3, v30, v31
	v_max3_f32 v3, v3, v32, v33
	v_max3_f32 v3, v3, v34, v35
	v_max3_f32 v3, v3, v198, v184
	v_max3_f32 v3, v3, v185, v186
	v_max3_f32 v3, v3, v187, v188
	v_max3_f32 v3, v3, v189, v190
	v_max3_f32 v3, v3, v191, v192
	v_max3_f32 v3, v3, v193, v194
	v_max3_f32 v3, v3, v195, v81
	v_max3_f32 v3, v3, v196, v197
	ds_bpermute_b32 v68, v172, v3
	s_waitcnt lgkmcnt(0)
; __device__ __forceinline__ void attn_phase(LAS unsigned char* lds, int vcu, int G, const bf16* Qp, const bf16* Kp, const bf16* Vt, const float* sinks, bf16* AO, int ldo, float* st) {
;     ...
;         mx = fmaxf(mx, __shfl_xor(mx, 32));
;         float l = 0.f;
; #pragma unroll
;         for (int kt = 0; kt < 5; ++kt)
; #pragma unroll
;             for (int r = 0; r < 16; ++r) { const float p = __builtin_amdgcn_exp2f(s[kt][r] - mx); s[kt][r] = p; l += p; }
;         l += __shfl_xor(l, 32);
;         l += __builtin_amdgcn_exp2f(sk - mx);
	v_max_f32_e32 v68, v68, v68
	v_max_f32_e32 v199, v3, v68
	v_sub_f32_e32 v3, v52, v199
	v_sub_f32_e32 v52, v53, v199
	v_exp_f32_e32 v181, v3
	v_sub_f32_e32 v53, v54, v199
	v_exp_f32_e32 v182, v52
	v_sub_f32_e32 v54, v55, v199
	v_exp_f32_e32 v179, v53
	v_sub_f32_e32 v55, v56, v199
	v_exp_f32_e32 v180, v54
	v_sub_f32_e32 v56, v57, v199
	v_exp_f32_e32 v177, v55
	v_add_f32_e32 v52, 0, v181
	v_sub_f32_e32 v57, v58, v199
	v_exp_f32_e32 v178, v56
	v_add_f32_e32 v52, v182, v52
	v_sub_f32_e32 v58, v59, v199
	v_sub_f32_e32 v74, v11, v199
	v_exp_f32_e32 v11, v57
	v_add_f32_e32 v52, v179, v52
	v_sub_f32_e32 v59, v60, v199
	v_sub_f32_e32 v75, v12, v199
	v_exp_f32_e32 v12, v58
	v_add_f32_e32 v52, v180, v52
	v_sub_f32_e32 v60, v61, v199
	v_sub_f32_e32 v72, v9, v199
	v_exp_f32_e32 v9, v59
	v_add_f32_e32 v52, v177, v52
	v_sub_f32_e32 v61, v62, v199
	v_sub_f32_e32 v73, v10, v199
	v_exp_f32_e32 v10, v60
	v_add_f32_e32 v52, v178, v52
	v_sub_f32_e32 v62, v63, v199
	v_sub_f32_e32 v70, v7, v199
	v_exp_f32_e32 v7, v61
	v_add_f32_e32 v52, v11, v52
	v_sub_f32_e32 v63, v64, v199
	v_sub_f32_e32 v71, v8, v199
	v_exp_f32_e32 v8, v62
	v_add_f32_e32 v52, v12, v52
	v_sub_f32_e32 v64, v65, v199
	v_sub_f32_e32 v68, v5, v199
	v_exp_f32_e32 v5, v63
	v_add_f32_e32 v52, v9, v52
	v_sub_f32_e32 v65, v66, v199
	v_sub_f32_e32 v69, v6, v199
	v_exp_f32_e32 v6, v64
	v_add_f32_e32 v52, v10, v52
	v_sub_f32_e32 v66, v67, v199
	v_exp_f32_e32 v3, v65
	v_add_f32_e32 v52, v7, v52
	v_sub_f32_e32 v67, v4, v199
	v_exp_f32_e32 v4, v66
	v_add_f32_e32 v52, v8, v52
	v_exp_f32_e32 v168, v67
	v_add_f32_e32 v52, v5, v52
	v_exp_f32_e32 v169, v68
	v_add_f32_e32 v52, v6, v52
	v_exp_f32_e32 v165, v69
	v_add_f32_e32 v52, v3, v52
	v_exp_f32_e32 v166, v70
	v_add_f32_e32 v52, v4, v52
	v_exp_f32_e32 v162, v71
	v_add_f32_e32 v52, v168, v52
	v_exp_f32_e32 v163, v72
	v_add_f32_e32 v52, v169, v52
	v_exp_f32_e32 v160, v73
	v_add_f32_e32 v52, v165, v52
	v_exp_f32_e32 v161, v74
	v_add_f32_e32 v52, v166, v52
	v_add_f32_e32 v52, v162, v52
	v_exp_f32_e32 v123, v75
	v_sub_f32_e32 v13, v13, v199
	v_add_f32_e32 v52, v163, v52
	v_exp_f32_e32 v164, v13
	v_sub_f32_e32 v13, v14, v199
	v_add_f32_e32 v52, v160, v52
	v_exp_f32_e32 v167, v13
	v_sub_f32_e32 v13, v15, v199
	v_add_f32_e32 v52, v161, v52
	v_exp_f32_e32 v170, v13
	v_sub_f32_e32 v14, v16, v199
	v_add_f32_e32 v13, v123, v52
	v_exp_f32_e32 v171, v14
	v_sub_f32_e32 v14, v17, v199
	v_add_f32_e32 v13, v164, v13
	v_exp_f32_e32 v174, v14
	v_sub_f32_e32 v14, v18, v199
	v_add_f32_e32 v13, v167, v13
	v_exp_f32_e32 v175, v14
	v_sub_f32_e32 v14, v19, v199
	v_add_f32_e32 v13, v170, v13
	v_exp_f32_e32 v176, v14
	v_sub_f32_e32 v14, v36, v199
	v_add_f32_e32 v13, v171, v13
	v_exp_f32_e32 v111, v14
	v_sub_f32_e32 v14, v37, v199
	v_add_f32_e32 v13, v174, v13
	v_exp_f32_e32 v112, v14
	v_sub_f32_e32 v14, v38, v199
	v_add_f32_e32 v13, v175, v13
	v_exp_f32_e32 v113, v14
	v_sub_f32_e32 v14, v39, v199
	v_add_f32_e32 v13, v176, v13
	v_exp_f32_e32 v115, v14
	v_sub_f32_e32 v14, v40, v199
	v_add_f32_e32 v13, v111, v13
	v_exp_f32_e32 v119, v14
	v_sub_f32_e32 v14, v41, v199
	v_add_f32_e32 v13, v112, v13
	v_exp_f32_e32 v120, v14
	v_sub_f32_e32 v14, v42, v199
	v_add_f32_e32 v13, v113, v13
	v_exp_f32_e32 v121, v14
	v_sub_f32_e32 v14, v43, v199
	v_add_f32_e32 v13, v115, v13
	v_exp_f32_e32 v122, v14
	v_sub_f32_e32 v14, v44, v199
	v_add_f32_e32 v13, v119, v13
	v_exp_f32_e32 v83, v14
	v_sub_f32_e32 v14, v45, v199
	v_add_f32_e32 v13, v120, v13
	v_exp_f32_e32 v108, v14
	v_sub_f32_e32 v14, v46, v199
	v_add_f32_e32 v13, v121, v13
	v_exp_f32_e32 v109, v14
	v_sub_f32_e32 v14, v47, v199
	v_add_f32_e32 v13, v122, v13
	v_exp_f32_e32 v110, v14
	v_sub_f32_e32 v14, v48, v199
	v_add_f32_e32 v13, v83, v13
	v_exp_f32_e32 v114, v14
	v_sub_f32_e32 v14, v49, v199
	v_add_f32_e32 v13, v108, v13
	v_exp_f32_e32 v116, v14
	v_sub_f32_e32 v14, v50, v199
	v_add_f32_e32 v13, v109, v13
	v_exp_f32_e32 v117, v14
	v_sub_f32_e32 v14, v51, v199
	v_add_f32_e32 v13, v110, v13
	v_exp_f32_e32 v118, v14
	v_sub_f32_e32 v14, v20, v199
	v_add_f32_e32 v13, v114, v13
	v_exp_f32_e32 v70, v14
	v_sub_f32_e32 v14, v21, v199
	v_add_f32_e32 v13, v116, v13
	v_exp_f32_e32 v71, v14
	v_sub_f32_e32 v14, v22, v199
	v_add_f32_e32 v13, v117, v13
	v_exp_f32_e32 v72, v14
	v_sub_f32_e32 v14, v23, v199
	v_add_f32_e32 v13, v118, v13
	v_exp_f32_e32 v74, v14
	v_sub_f32_e32 v14, v24, v199
	v_add_f32_e32 v13, v70, v13
	v_exp_f32_e32 v78, v14
	v_sub_f32_e32 v14, v25, v199
	v_add_f32_e32 v13, v71, v13
	v_exp_f32_e32 v79, v14
	v_sub_f32_e32 v14, v26, v199
	v_add_f32_e32 v13, v72, v13
	v_exp_f32_e32 v80, v14
	v_sub_f32_e32 v14, v27, v199
	v_add_f32_e32 v13, v74, v13
	v_exp_f32_e32 v82, v14
	v_sub_f32_e32 v14, v28, v199
	v_add_f32_e32 v13, v78, v13
	v_exp_f32_e32 v66, v14
	v_sub_f32_e32 v14, v29, v199
	v_add_f32_e32 v13, v79, v13
	v_exp_f32_e32 v67, v14
	v_sub_f32_e32 v14, v30, v199
	v_add_f32_e32 v13, v80, v13
	v_exp_f32_e32 v68, v14
	v_sub_f32_e32 v14, v31, v199
	v_add_f32_e32 v13, v82, v13
	v_exp_f32_e32 v69, v14
	v_sub_f32_e32 v14, v32, v199
	v_add_f32_e32 v13, v66, v13
	v_exp_f32_e32 v73, v14
	v_sub_f32_e32 v14, v33, v199
	v_add_f32_e32 v13, v67, v13
	v_exp_f32_e32 v75, v14
	v_sub_f32_e32 v14, v34, v199
	v_add_f32_e32 v13, v68, v13
	v_exp_f32_e32 v76, v14
	v_sub_f32_e32 v14, v35, v199
	v_add_f32_e32 v13, v69, v13
	v_exp_f32_e32 v77, v14
	v_sub_f32_e32 v14, v198, v199
	v_add_f32_e32 v13, v73, v13
	v_exp_f32_e32 v54, v14
	v_sub_f32_e32 v14, v184, v199
	v_add_f32_e32 v13, v75, v13
	v_exp_f32_e32 v55, v14
	v_sub_f32_e32 v14, v185, v199
	v_add_f32_e32 v13, v76, v13
	v_exp_f32_e32 v56, v14
	v_sub_f32_e32 v14, v186, v199
	v_add_f32_e32 v13, v77, v13
	v_exp_f32_e32 v58, v14
	v_sub_f32_e32 v14, v187, v199
	v_add_f32_e32 v13, v54, v13
	v_exp_f32_e32 v62, v14
	v_sub_f32_e32 v14, v188, v199
	v_add_f32_e32 v13, v55, v13
	v_exp_f32_e32 v63, v14
	v_sub_f32_e32 v14, v189, v199
	v_add_f32_e32 v13, v56, v13
	v_exp_f32_e32 v64, v14
	v_sub_f32_e32 v14, v190, v199
	v_add_f32_e32 v13, v58, v13
	v_exp_f32_e32 v65, v14
	v_sub_f32_e32 v14, v191, v199
	v_add_f32_e32 v13, v62, v13
	v_exp_f32_e32 v50, v14
	v_sub_f32_e32 v14, v192, v199
	v_add_f32_e32 v13, v63, v13
	v_exp_f32_e32 v51, v14
	v_sub_f32_e32 v14, v193, v199
	v_add_f32_e32 v13, v64, v13
	v_exp_f32_e32 v52, v14
	v_sub_f32_e32 v14, v194, v199
	v_add_f32_e32 v13, v65, v13
	v_exp_f32_e32 v53, v14
	v_sub_f32_e32 v14, v195, v199
	v_add_f32_e32 v13, v50, v13
	v_exp_f32_e32 v57, v14
	v_sub_f32_e32 v14, v81, v199
	v_add_f32_e32 v13, v51, v13
	v_exp_f32_e32 v59, v14
	v_sub_f32_e32 v14, v196, v199
	v_add_f32_e32 v13, v52, v13
	v_exp_f32_e32 v60, v14
	v_sub_f32_e32 v14, v197, v199
	v_add_f32_e32 v13, v53, v13
	v_exp_f32_e32 v61, v14
	v_add_f32_e32 v13, v57, v13
	v_add_f32_e32 v13, v59, v13
	v_add_f32_e32 v13, v60, v13
	v_add_f32_e32 v13, v61, v13
	ds_bpermute_b32 v14, v172, v13
	v_fma_f32 v15, v183, s3, -v199
	v_exp_f32_e32 v15, v15
	s_waitcnt lgkmcnt(0)
; __device__ __forceinline__ unsigned cvt_pk_bf16(float lo, float hi) { unsigned r; asm volatile("v_cvt_pk_bf16_f32 %0, %1, %2" : "=v"(r) : "v"(lo), "v"(hi)); return r; }
; #define LAS __attribute__((address_space(3)))
; __device__ __forceinline__ void attn_phase(LAS unsigned char* lds, int vcu, int G, const bf16* Qp, const bf16* Kp, const bf16* Vt, const float* sinks, bf16* AO, int ldo, float* st) {
;     ...
;         for (int i = 0; i < 3; ++i) { const int c = tid + 512 * i, row = c >> 3, ch = c & 7, key = q0 - 128 + row;
;             if (key >= 0) *(LAS v4u*)(lds + row * AT_KROW + ch * 16) = kv[i]; }
; #pragma unroll
;         for (int i = 0; i < 3; ++i) { const int c = tid + 512 * i, d = c / 24, ch = c - d * 24, key0 = q0 - 128 + 8 * ch;
;             if (key0 >= 0) { LAS u64* p = (LAS u64*)(lds + AT_V_OFF + d * AT_VROW + ch * 16); p[0] = ((u64)vv[i].y << 32) | vv[i].x; p[1] = ((u64)vv[i].w << 32) | vv[i].z; } }
;     ...
;         const float inv = 1.0f / l;
;         f32x16 o[2];
; #pragma unroll
;         for (int d = 0; d < 2; ++d)
; #pragma unroll
;             for (int r = 0; r < 16; ++r) o[d][r] = 0.f;
; #pragma unroll
;         for (int kt = 0; kt < 5; ++kt) {
;             if (kt + qsub >= jt0) {
; #pragma unroll
;                 for (int s2 = 0; s2 < 2; ++s2) {
;                     v4u pw; pw.x = cvt_pk_bf16(s[kt][8 * s2 + 0] * inv, s[kt][8 * s2 + 1] * inv); pw.y = cvt_pk_bf16(s[kt][8 * s2 + 2] * inv, s[kt][8 * s2 + 3] * inv);
;                     pw.z = cvt_pk_bf16(s[kt][8 * s2 + 4] * inv, s[kt][8 * s2 + 5] * inv); pw.w = cvt_pk_bf16(s[kt][8 * s2 + 6] * inv, s[kt][8 * s2 + 7] * inv);
;                     const bf16x8 pf = __builtin_bit_cast(bf16x8, pw);
; #pragma unroll
;                     for (int dh = 0; dh < 2; ++dh) {
;                         const LAS u64* vp = (const LAS u64*)(lds + AT_V_OFF + (dh * 32 + r32) * AT_VROW + (32 * (kt + qsub) + 16 * s2 + 4 * hi) * 2);
;                         const u64 lo = vp[0], hi8 = vp[2];
;                         const v4u vw = (v4u){(unsigned)lo, (unsigned)(lo >> 32), (unsigned)hi8, (unsigned)(hi8 >> 32)};
;                         o[dh] = __builtin_amdgcn_mfma_f32_32x32x16_bf16(__builtin_bit_cast(bf16x8, vw), pf, o[dh], 0, 0, 0);
;                     }
;                 }
;             }
	v_add_f32_e32 v13, v13, v14
	v_add_f32_e32 v13, v15, v13
	v_div_scale_f32 v14, vcc, v13, v13, 1.0
	v_rcp_f32_e32 v15, v14
	s_nop 0
	v_fma_f32 v16, -v14, v15, 1.0
	v_fmac_f32_e32 v15, v16, v15
	v_div_scale_f32 v16, vcc, 1.0, v13, 1.0
	v_mul_f32_e32 v17, v16, v15
	v_fma_f32 v18, -v14, v17, v16
	v_fmac_f32_e32 v17, v18, v15
	v_fma_f32 v14, -v14, v17, v16
	v_div_fmas_f32 v14, v14, v15, v17
	s_and_b64 vcc, exec, s[64:65]
	v_div_fixup_f32 v81, v14, v13, 1.0
	s_cbranch_vccnz .LBB0_692
	v_mul_f32_e32 v13, v181, v81
	v_mul_f32_e32 v14, v182, v81
	v_cvt_pk_bf16_f32 v14, v13, v14
	v_mul_f32_e32 v13, v179, v81
	v_mul_f32_e32 v15, v180, v81
	v_cvt_pk_bf16_f32 v15, v13, v15
	v_mul_f32_e32 v13, v177, v81
	v_mul_f32_e32 v16, v178, v81
	v_add_u32_e32 v177, 0x6800, v153
	v_cvt_pk_bf16_f32 v16, v13, v16
	v_mul_f32_e32 v11, v11, v81
	v_mul_f32_e32 v12, v12, v81
	v_cvt_pk_bf16_f32 v17, v11, v12
	ds_read2_b64 v[18:21], v177 offset0:128 offset1:130
	v_add_u32_e32 v178, 0x9800, v153
	v_mul_f32_e32 v10, v10, v81
	v_mul_f32_e32 v7, v7, v81
	v_mul_f32_e32 v5, v5, v81
	v_mul_f32_e32 v6, v6, v81
	v_mul_f32_e32 v4, v4, v81
	s_waitcnt lgkmcnt(0)
	v_mfma_f32_32x32x16_bf16 v[34:49], v[18:21], v[14:17], 0
	ds_read2_b64 v[18:21], v178 offset0:160 offset1:162
	v_mul_f32_e32 v9, v9, v81
	v_cvt_pk_bf16_f32 v10, v9, v10
	v_mul_f32_e32 v8, v8, v81
	v_cvt_pk_bf16_f32 v11, v7, v8
	v_cvt_pk_bf16_f32 v12, v5, v6
	v_mul_f32_e32 v3, v3, v81
	v_cvt_pk_bf16_f32 v13, v3, v4
	ds_read2_b64 v[4:7], v177 offset0:132 offset1:134
	s_waitcnt lgkmcnt(0)
	v_mfma_f32_32x32x16_bf16 v[34:49], v[4:7], v[10:13], v[34:49]
	ds_read2_b64 v[4:7], v178 offset0:164 offset1:166
	v_mfma_f32_32x32x16_bf16 v[18:33], v[18:21], v[14:17], 0
	s_waitcnt lgkmcnt(0)
	v_mfma_f32_32x32x16_bf16 v[18:33], v[4:7], v[10:13], v[18:33]
	s_and_b64 vcc, exec, s[62:63]
	s_cbranch_vccz .LBB0_693
	s_branch .LBB0_694
.LBB0_687:
	s_waitcnt vmcnt(0)
	ds_write_b128 v142, v[200:203]
	s_or_b64 exec, exec, s[62:63]
	s_and_saveexec_b64 s[62:63], s[18:19]
	s_cbranch_execz .LBB0_665
.LBB0_688:
	s_waitcnt vmcnt(0)
	ds_write_b128 v143, v[204:207]
	s_or_b64 exec, exec, s[62:63]
	s_and_saveexec_b64 s[62:63], s[20:21]
	s_cbranch_execz .LBB0_666
.LBB0_689:
	s_waitcnt vmcnt(0)
	ds_write_b128 v144, v[208:211]
	s_or_b64 exec, exec, s[62:63]
	s_and_saveexec_b64 s[62:63], s[22:23]
	s_cbranch_execz .LBB0_667
.LBB0_690:
	s_waitcnt vmcnt(0)
	ds_write2_b64 v145, v[212:213], v[214:215] offset1:1
	s_or_b64 exec, exec, s[62:63]
	s_and_saveexec_b64 s[62:63], s[24:25]
	s_cbranch_execz .LBB0_668
.LBB0_691:
	s_waitcnt vmcnt(0)
	ds_write2_b64 v146, v[216:217], v[218:219] offset1:1
	s_or_b64 exec, exec, s[62:63]
	s_and_saveexec_b64 s[62:63], s[26:27]
	s_cbranch_execnz .LBB0_669
	s_branch .LBB0_670
